# baseline (speedup 1.0000x reference)
; DI float bf2f(short b) { return __uint_as_float(((unsigned)(unsigned short)b) << 16); }
; DI bf16x8 pack8(const float* a) { u32x4 w = {cvtpk(a[0], a[1]), cvtpk(a[2], a[3]), cvtpk(a[4], a[5]), cvtpk(a[6], a[7])}; return *reinterpret_cast<bf16x8*>(&w); }
; DI void attn_item_dma(const u16* Qb, const u16* Kh, const u16* Vh, const u16* Rh, u16* Ob, int seq, const float* rope, int pos0, char* lds) {
;     ...
;   const u16* Qw = Qb + (size_t)(wid * 32 + r32) * LDQ + hi * 8;
; #pragma unroll
;   for (int d0 = 0; d0 < 8; ++d0) qr[d0] = ld8(Qw + d0 * 16);
;   { const float* rp = rope + (size_t)(pos0 + wid * 32 + r32) * 64 + hi * 8;
; #pragma unroll
;     for (int f = 0; f < 2; ++f) {
;       const bf16x8 x1 = ld8(Qw + (8 + f) * 16), x2 = ld8(Qw + (10 + f) * 16);
;       const float4 c0 = *reinterpret_cast<const float4*>(rp + f * 16), c1 = *reinterpret_cast<const float4*>(rp + f * 16 + 4);
;       const float4 s0 = *reinterpret_cast<const float4*>(rp + 32 + f * 16), s1 = *reinterpret_cast<const float4*>(rp + 32 + f * 16 + 4);
;       const float cc[8] = {c0.x, c0.y, c0.z, c0.w, c1.x, c1.y, c1.z, c1.w}, ss[8] = {s0.x, s0.y, s0.z, s0.w, s1.x, s1.y, s1.z, s1.w};
;       float o1[8], o2[8];
; #pragma unroll
;       for (int j = 0; j < 8; ++j) { const float a = bf2f(x1[j]), b = bf2f(x2[j]); o1[j] = a * cc[j] - b * ss[j]; o2[j] = a * ss[j] + b * cc[j]; }
;       qr[8 + f] = pack8(o1); qr[10 + f] = pack8(o2);
;     } }
;   int voK0, voV0, voR;
;   { const int row = tid >> 4, cch = (tid & 15) ^ (row & 7); voK0 = row * 4096 + cch * 16; }
;   { const int row = tid >> 3, cch = (tid & 7) ^ ((row >> 1) & 7); voR = row * 128 + cch * 16; }
;   { const int sub = tid >> 5, wi = tid & 31, kk = (sub >> 2) * 8 + (wi >> 2), c = (sub & 3) * 32 + (wi & 3) * 8;
;     const int k = (kk & ~0xC) | ((kk & 4) << 1) | ((kk & 8) >> 1); voV0 = k * 4096 + c * 2; }
;   const char* Kb = (const char*)Kh; const char* Vb = (const char*)Vh; const char* Rb = (const char*)Rh;
;     ...
;   const int vb0 = (int)(uintptr_t)lds + v_rd_base(lane);
;   int ko[4], ro[4];
; #pragma unroll
;   for (int i = 0; i < 4; ++i) { ko[i] = r32 * 256 + ((i * 32 + hi * 16) ^ ((r32 & 7) << 4)); ro[i] = r32 * 128 + ((i * 32 + hi * 16) ^ (((r32 >> 1) & 7) << 4)); }
;   f32x16 pA0, pA1, pB0, pB1; float mnA, mnB, alA, alB; bf16x8 pa0, pa1, pa2, pa3; const int NT = seq / 64;
;   __syncthreads();
;   DMA(0, 0); DMA(1, 1); VWAIT(); __syncthreads();
.LBB0_121:
	s_and_b32 s2, s50, 7
	s_lshl_b32 s6, s2, 9
	s_ashr_i32 s2, s59, 3
	s_abs_i32 s12, s2
	s_mul_hi_u32 s13, s12, s58
	s_mul_i32 s36, s13, s54
	s_ashr_i32 s7, s59, 31
	s_sub_i32 s12, s12, s36
	s_and_b32 s60, s59, 7
	s_xor_b32 s7, s7, s55
	s_add_i32 s36, s13, 1
	s_sub_i32 s37, s12, s54
	s_cmp_ge_u32 s12, s54
	s_cselect_b32 s13, s36, s13
	s_cselect_b32 s12, s37, s12
	s_add_i32 s36, s13, 1
	s_cmp_ge_u32 s12, s54
	s_cselect_b32 s12, s36, s13
	s_xor_b32 s12, s12, s7
	s_sub_i32 s12, s12, s7
	s_mul_i32 s7, s12, s51
	s_sub_i32 s2, s2, s7
	s_waitcnt vmcnt(0)
	v_mov_b32_e32 v58, v232
	s_lshl_b32 s2, s2, 8
	s_ashr_i32 s13, s12, 31
	v_and_b32_e32 v170, 31, v58
	v_ashrrev_i32_e32 v10, 1, v58
	v_and_b32_e32 v146, 0xffffffe0, v10
	v_or_b32_e32 v0, s2, v170
	v_add_u32_e32 v0, v0, v146
	v_ashrrev_i32_e32 v1, 31, v0
	s_lshl_b64 s[36:37], s[12:13], s53
	s_ashr_i32 s7, s2, 31
	v_lshlrev_b64 v[0:1], 8, v[0:1]
	s_add_u32 s40, s36, s2
	v_lshl_add_u64 v[0:1], s[48:49], 0, v[0:1]
	v_and_b32_e32 v2, 32, v58
	v_mov_b32_e32 v3, v97
	s_addc_u32 s41, s37, s7
	v_lshl_add_u64 v[0:1], v[0:1], 0, v[2:3]
	s_mul_i32 s7, s41, 0xc00
	s_mul_hi_u32 s12, s40, 0xc00
	global_load_dwordx4 v[2:5], v[0:1], off offset:128
	global_load_dwordx4 v[6:9], v[0:1], off
	s_add_i32 s12, s12, s7
	s_mul_i32 s7, s40, 0xc00
	s_add_u32 s7, s46, s7
	s_addc_u32 s13, s47, s12
	s_mul_i32 s2, s60, 0x180
	s_add_u32 s12, s7, s2
	s_addc_u32 s13, s13, 0
	s_movk_i32 s2, 0xffe0
	v_bfe_u32 v171, v58, 5, 1
	v_bfi_b32 v12, s2, v10, v58
	v_mov_b64_e32 v[10:11], s[12:13]
	s_movk_i32 s2, 0xc00
	v_mad_i64_i32 v[10:11], s[12:13], v12, s2, v[10:11]
	v_lshlrev_b32_e32 v96, 4, v171
	v_lshl_add_u64 v[26:27], v[10:11], 0, v[96:97]
	global_load_dwordx4 v[10:13], v[0:1], off offset:144
	global_load_dwordx4 v[14:17], v[0:1], off offset:16
	global_load_dwordx4 v[18:21], v[26:27], off offset:256
	global_load_dwordx4 v[22:25], v[26:27], off offset:320
	global_load_dwordx4 v[134:137], v[26:27], off
	global_load_dwordx4 v[130:133], v[26:27], off offset:32
	global_load_dwordx4 v[126:129], v[26:27], off offset:64
	global_load_dwordx4 v[114:117], v[26:27], off offset:96
	global_load_dwordx4 v[110:113], v[26:27], off offset:128
	global_load_dwordx4 v[106:109], v[26:27], off offset:160
	global_load_dwordx4 v[102:105], v[26:27], off offset:192
	global_load_dwordx4 v[98:101], v[26:27], off offset:224
	s_lshl_b64 s[38:39], s[36:37], 12
	s_add_u32 s2, s14, s38
	v_lshlrev_b32_e32 v82, 3, v58
	s_addc_u32 s7, s15, s39
	s_lshl_b32 s12, s60, 9
	v_lshlrev_b32_e32 v175, 4, v58
	v_bfe_u32 v59, v58, 2, 2
	s_add_u32 s44, s2, s12
	s_movk_i32 s2, 0x70
	s_addc_u32 s45, s7, 0
	v_add_u32_e32 v178, 16, v175
	s_mov_b64 s[12:13], 0x20100
	v_mov_b32_e32 v49, v97
	s_lshl_b64 s[42:43], s[36:37], 7
	s_add_u32 s36, s56, s42
	s_addc_u32 s37, s57, s43
	v_mov_b32_e32 v51, v97
	v_ashrrev_i32_e32 v238, 4, v58
	v_lshrrev_b32_e32 v241, 1, v58
	v_and_b32_e32 v239, 15, v58
	v_and_b32_e32 v242, 0x60, v58
	v_and_b32_e32 v241, 8, v241
	v_lshrrev_b32_e32 v243, 1, v238
	v_bitop3_b32 v239, v238, v239, 7 bitop3:0x6c
	v_and_or_b32 v242, v82, 24, v242
	v_and_b32_e32 v60, 4, v243
	v_and_or_b32 v61, v238, -16, v241
	v_lshlrev_b32_e32 v238, 12, v238
	v_xor_b32_e32 v240, v175, v58
	v_or3_b32 v241, v61, v59, v60
	v_lshlrev_b32_e32 v242, 1, v242
	v_lshl_or_b32 v48, v239, 4, v238
	v_and_b32_e32 v238, 0xffffff80, v175
	v_and_or_b32 v50, v240, s2, v238
	v_lshl_or_b32 v238, v241, 12, v242
	v_mov_b32_e32 v239, v97
	v_lshl_add_u64 v[52:53], s[44:45], 0, v[238:239]
	v_readfirstlane_b32 s2, v178
	v_add_u32_e32 v240, 0x2000, v178
	v_lshl_add_u64 v[238:239], v[52:53], 0, s[4:5]
	s_mov_b32 m0, s2
	v_readfirstlane_b32 s2, v240
	s_barrier
	global_load_lds_dwordx4 v[238:239], off
	v_lshl_add_u64 v[238:239], v[52:53], 0, s[12:13]
	s_mov_b32 m0, s2
	v_add_u32_e32 v240, 0x6000, v178
	global_load_lds_dwordx4 v[238:239], off
	v_add_u32_e32 v238, 0x4000, v178
	v_lshl_add_u64 v[54:55], s[44:45], 0, v[48:49]
	v_readfirstlane_b32 s2, v238
	s_mov_b32 m0, s2
	s_mov_b64 s[12:13], 0x20000
	v_readfirstlane_b32 s2, v240
	global_load_lds_dwordx4 v48, s[44:45]
	v_lshl_add_u64 v[238:239], v[54:55], 0, s[12:13]
	s_mov_b32 m0, s2
	v_add_u32_e32 v240, 0xa000, v178
	global_load_lds_dwordx4 v[238:239], off
	v_add_u32_e32 v238, 0x8000, v178
	s_mov_b64 s[12:13], 0x40100
	v_readfirstlane_b32 s2, v238
	s_mov_b32 m0, s2
	v_readfirstlane_b32 s2, v240
	v_add_u32_e32 v240, 0xc000, v178
	global_load_lds_dwordx4 v50, s[36:37]
	v_lshl_add_u64 v[238:239], v[52:53], 0, s[12:13]
	s_mov_b32 m0, s2
	s_mov_b64 s[12:13], 0x60100
	v_readfirstlane_b32 s2, v240
	v_add_u32_e32 v240, 0xe000, v178
	global_load_lds_dwordx4 v[238:239], off
	v_lshl_add_u64 v[238:239], v[52:53], 0, s[12:13]
	s_mov_b32 m0, s2
	s_mov_b64 s[12:13], 0x40000
	v_readfirstlane_b32 s2, v240
	v_add_u32_e32 v240, 0x10000, v178
	global_load_lds_dwordx4 v[238:239], off
	v_lshl_add_u64 v[238:239], v[54:55], 0, s[12:13]
	s_mov_b32 m0, s2
	s_mov_b64 s[12:13], 0x60000
	v_readfirstlane_b32 s2, v240
	v_add_u32_e32 v240, 0x12000, v178
	v_lshl_add_u64 v[56:57], s[36:37], 0, v[50:51]
	global_load_lds_dwordx4 v[238:239], off
	v_lshl_add_u64 v[238:239], v[54:55], 0, s[12:13]
	s_mov_b32 m0, s2
	s_mov_b64 s[12:13], 0x2000
	v_readfirstlane_b32 s2, v240
	global_load_lds_dwordx4 v[238:239], off
	v_lshl_add_u64 v[238:239], v[56:57], 0, s[12:13]
	s_mov_b32 m0, s2
	s_nop 0
	global_load_lds_dwordx4 v[238:239], off
	v_lshlrev_b32_e32 v74, 8, v170
	v_and_b32_e32 v75, 0x70, v175
	v_bitop3_b32 v176, v96, v74, v75 bitop3:0xde
	v_or_b32_e32 v83, 32, v96
	v_bitop3_b32 v179, v83, v74, v75 bitop3:0xde
	v_add_u32_e32 v76, 16, v179
	v_or_b32_e32 v84, 64, v96
	v_bitop3_b32 v180, v84, v74, v75 bitop3:0xde
	v_add_u32_e32 v85, 16, v180
	v_or_b32_e32 v86, 0x60, v96
	v_bitop3_b32 v181, v86, v74, v75 bitop3:0xde
	v_add_u32_e32 v87, 16, v181
	s_mov_b32 s84, s85
	s_mov_b32 s86, s85
	s_mov_b32 s87, s85
	s_mov_b32 s88, s85
	s_mov_b32 s89, s85
	s_mov_b32 s90, s85
	s_mov_b32 s91, s85
	s_mov_b32 s92, s85
	s_mov_b32 s93, s85
	s_mov_b32 s94, s85
	s_mov_b32 s95, s85
	s_mov_b32 s96, s85
	s_mov_b32 s97, s85
	s_mov_b32 s98, s85
	s_mov_b32 s99, s85
	s_mov_b32 s61, 1
	v_mov_b32_e32 v173, 0
	s_waitcnt vmcnt(23)
; DI float bf2f(short b) { return __uint_as_float(((unsigned)(unsigned short)b) << 16); }
; DI bf16x8 pack8(const float* a) { u32x4 w = {cvtpk(a[0], a[1]), cvtpk(a[2], a[3]), cvtpk(a[4], a[5]), cvtpk(a[6], a[7])}; return *reinterpret_cast<bf16x8*>(&w); }
; DI void attn_item_dma(const u16* Qb, const u16* Kh, const u16* Vh, const u16* Rh, u16* Ob, int seq, const float* rope, int pos0, char* lds) {
;     ...
;   { const float* rp = rope + (size_t)(pos0 + wid * 32 + r32) * 64 + hi * 8;
; #pragma unroll
;     for (int f = 0; f < 2; ++f) {
;       const bf16x8 x1 = ld8(Qw + (8 + f) * 16), x2 = ld8(Qw + (10 + f) * 16);
;       const float4 c0 = *reinterpret_cast<const float4*>(rp + f * 16), c1 = *reinterpret_cast<const float4*>(rp + f * 16 + 4);
;       const float4 s0 = *reinterpret_cast<const float4*>(rp + 32 + f * 16), s1 = *reinterpret_cast<const float4*>(rp + 32 + f * 16 + 4);
;       const float cc[8] = {c0.x, c0.y, c0.z, c0.w, c1.x, c1.y, c1.z, c1.w}, ss[8] = {s0.x, s0.y, s0.z, s0.w, s1.x, s1.y, s1.z, s1.w};
;       float o1[8], o2[8];
; #pragma unroll
;       for (int j = 0; j < 8; ++j) { const float a = bf2f(x1[j]), b = bf2f(x2[j]); o1[j] = a * cc[j] - b * ss[j]; o2[j] = a * ss[j] + b * cc[j]; }
;       qr[8 + f] = pack8(o1); qr[10 + f] = pack8(o2);
;     } }
	v_mov_b32_e32 v28, v2
	s_waitcnt vmcnt(22)
	v_mov_b32_e32 v29, v6
	v_mov_b32_e32 v30, v6
	v_mov_b32_e32 v31, v2
	v_mov_b32_e32 v6, v3
	v_mov_b32_e32 v2, v7
	v_mov_b32_e32 v32, v4
	s_waitcnt vmcnt(21)
	v_mov_b32_e32 v36, v10
	s_waitcnt vmcnt(20)
	v_mov_b32_e32 v37, v14
	s_waitcnt vmcnt(19)
	v_and_b32_e32 v41, 0xffff0000, v18
	s_waitcnt vmcnt(18)
	v_and_b32_e32 v40, 0xffff0000, v22
	v_lshlrev_b32_e32 v39, 16, v18
	v_lshlrev_b32_e32 v38, 16, v22
	v_lshlrev_b32_e32 v42, 16, v23
	v_and_b32_e32 v18, 0xffff0000, v23
	v_lshlrev_b32_e32 v23, 16, v20
	v_lshlrev_b32_e32 v22, 16, v24
	v_pk_mul_f32 v[6:7], v[6:7], v[40:41]
	v_pk_mul_f32 v[2:3], v[2:3], v[40:41]
	v_mov_b32_e32 v33, v8
	v_mov_b32_e32 v34, v8
	v_mov_b32_e32 v35, v4
	v_mov_b32_e32 v8, v5
	v_mov_b32_e32 v4, v9
	v_lshlrev_b32_e32 v43, 16, v19
	v_and_b32_e32 v19, 0xffff0000, v19
	v_pk_mul_f32 v[30:31], v[30:31], v[38:39]
	v_sub_f32_e32 v6, v7, v6
	v_add_f32_e32 v7, v2, v3
	v_pk_mul_f32 v[2:3], v[36:37], v[22:23]
	v_pk_mul_f32 v[8:9], v[8:9], v[18:19]
	v_pk_mul_f32 v[4:5], v[4:5], v[18:19]
	v_add_f32_e32 v19, v30, v31
	v_sub_f32_e32 v30, v3, v2
	v_mov_b32_e32 v2, v14
	v_mov_b32_e32 v3, v10
	v_pk_mul_f32 v[2:3], v[2:3], v[22:23]
	v_mov_b32_e32 v14, v11
	v_add_f32_e32 v22, v2, v3
	v_and_b32_e32 v3, 0xffff0000, v20
	v_and_b32_e32 v2, 0xffff0000, v24
	v_mov_b32_e32 v10, v15
	v_sub_f32_e32 v8, v9, v8
	v_add_f32_e32 v9, v4, v5
	v_pk_mul_f32 v[4:5], v[14:15], v[2:3]
	v_pk_mul_f32 v[2:3], v[10:11], v[2:3]
	v_sub_f32_e32 v14, v5, v4
	v_add_f32_e32 v10, v2, v3
	v_lshlrev_b32_e32 v3, 16, v21
	v_lshlrev_b32_e32 v2, 16, v25
	v_mov_b32_e32 v4, v12
	v_mov_b32_e32 v5, v16
	v_pk_mul_f32 v[4:5], v[4:5], v[2:3]
	v_pk_mul_f32 v[28:29], v[28:29], v[38:39]
	v_sub_f32_e32 v11, v5, v4
	v_mov_b32_e32 v4, v16
	v_mov_b32_e32 v5, v12
	v_pk_mul_f32 v[2:3], v[4:5], v[2:3]
	v_mov_b32_e32 v16, v13
	v_add_f32_e32 v15, v2, v3
	v_and_b32_e32 v3, 0xffff0000, v21
	v_and_b32_e32 v2, 0xffff0000, v25
	v_mov_b32_e32 v12, v17
	v_pk_mul_f32 v[4:5], v[16:17], v[2:3]
	v_pk_mul_f32 v[2:3], v[12:13], v[2:3]
	v_pk_mul_f32 v[32:33], v[32:33], v[42:43]
	v_pk_mul_f32 v[34:35], v[34:35], v[42:43]
	v_sub_f32_e32 v18, v29, v28
	v_sub_f32_e32 v4, v5, v4
	v_add_f32_e32 v2, v2, v3
	v_sub_f32_e32 v28, v33, v32
	v_add_f32_e32 v29, v34, v35
	v_cvt_pk_bf16_f32 v122, v18, v6
	v_cvt_pk_bf16_f32 v123, v28, v8
	v_cvt_pk_bf16_f32 v124, v30, v14
	v_cvt_pk_bf16_f32 v125, v11, v4
	v_cvt_pk_bf16_f32 v118, v19, v7
	v_cvt_pk_bf16_f32 v119, v29, v9
	v_cvt_pk_bf16_f32 v120, v22, v10
	v_cvt_pk_bf16_f32 v121, v15, v2
	global_load_dwordx4 v[2:5], v[26:27], off offset:288
	global_load_dwordx4 v[6:9], v[26:27], off offset:352
	global_load_dwordx4 v[10:13], v[0:1], off offset:192
	global_load_dwordx4 v[14:17], v[0:1], off offset:64
	global_load_dwordx4 v[18:21], v[0:1], off offset:208
	global_load_dwordx4 v[22:25], v[0:1], off offset:80
	s_waitcnt vmcnt(5)
	v_lshlrev_b32_e32 v1, 16, v2
	s_waitcnt vmcnt(4)
	v_lshlrev_b32_e32 v0, 16, v6
	s_waitcnt vmcnt(3)
	v_mov_b32_e32 v26, v10
	s_waitcnt vmcnt(2)
	v_mov_b32_e32 v27, v14
	v_mov_b32_e32 v28, v14
	v_mov_b32_e32 v29, v10
	v_pk_mul_f32 v[26:27], v[26:27], v[0:1]
	v_pk_mul_f32 v[0:1], v[28:29], v[0:1]
	v_and_b32_e32 v30, 0xffff0000, v6
	v_mov_b32_e32 v34, v12
	v_mov_b32_e32 v35, v16
	v_mov_b32_e32 v36, v16
	v_mov_b32_e32 v37, v12
	v_sub_f32_e32 v6, v27, v26
	v_add_f32_e32 v26, v0, v1
	v_and_b32_e32 v1, 0xffff0000, v3
	v_and_b32_e32 v0, 0xffff0000, v7
	v_mov_b32_e32 v16, v13
	v_mov_b32_e32 v12, v17
	v_and_b32_e32 v31, 0xffff0000, v2
	v_lshlrev_b32_e32 v33, 16, v3
	v_pk_mul_f32 v[2:3], v[16:17], v[0:1]
	v_pk_mul_f32 v[0:1], v[12:13], v[0:1]
	v_lshlrev_b32_e32 v32, 16, v7
	v_sub_f32_e32 v7, v3, v2
	v_add_f32_e32 v12, v0, v1
	v_lshlrev_b32_e32 v1, 16, v4
	v_lshlrev_b32_e32 v0, 16, v8
	s_waitcnt vmcnt(1)
	v_mov_b32_e32 v2, v18
	s_waitcnt vmcnt(0)
	v_mov_b32_e32 v3, v22
	v_pk_mul_f32 v[2:3], v[2:3], v[0:1]
	v_mov_b32_e32 v14, v11
	v_sub_f32_e32 v13, v3, v2
	v_mov_b32_e32 v2, v22
	v_mov_b32_e32 v3, v18
	v_pk_mul_f32 v[0:1], v[2:3], v[0:1]
	v_mov_b32_e32 v22, v19
	v_add_f32_e32 v16, v0, v1
	v_and_b32_e32 v1, 0xffff0000, v4
	v_and_b32_e32 v0, 0xffff0000, v8
	v_mov_b32_e32 v18, v23
	v_pk_mul_f32 v[2:3], v[22:23], v[0:1]
	v_pk_mul_f32 v[0:1], v[18:19], v[0:1]
	v_sub_f32_e32 v4, v3, v2
	v_add_f32_e32 v8, v0, v1
	v_lshlrev_b32_e32 v1, 16, v5
	v_lshlrev_b32_e32 v0, 16, v9
	v_mov_b32_e32 v2, v20
	v_mov_b32_e32 v3, v24
	v_pk_mul_f32 v[2:3], v[2:3], v[0:1]
	v_mov_b32_e32 v10, v15
	v_sub_f32_e32 v17, v3, v2
	v_mov_b32_e32 v2, v24
	v_mov_b32_e32 v3, v20
	v_pk_mul_f32 v[0:1], v[2:3], v[0:1]
	v_mov_b32_e32 v24, v21
	v_add_f32_e32 v18, v0, v1
	v_and_b32_e32 v1, 0xffff0000, v5
	v_and_b32_e32 v0, 0xffff0000, v9
	v_mov_b32_e32 v20, v25
	v_pk_mul_f32 v[2:3], v[24:25], v[0:1]
	v_pk_mul_f32 v[0:1], v[20:21], v[0:1]
	v_pk_mul_f32 v[14:15], v[14:15], v[30:31]
	v_pk_mul_f32 v[10:11], v[10:11], v[30:31]
	v_pk_mul_f32 v[28:29], v[34:35], v[32:33]
	v_pk_mul_f32 v[30:31], v[36:37], v[32:33]
	v_add_f32_e32 v0, v0, v1
	v_sub_f32_e32 v14, v15, v14
	v_add_f32_e32 v10, v10, v11
	v_sub_f32_e32 v11, v29, v28
	v_add_f32_e32 v15, v30, v31
	v_sub_f32_e32 v2, v3, v2
	v_cvt_pk_bf16_f32 v142, v6, v14
	v_cvt_pk_bf16_f32 v143, v11, v7
	v_cvt_pk_bf16_f32 v144, v13, v4
	v_cvt_pk_bf16_f32 v145, v17, v2
	v_cvt_pk_bf16_f32 v138, v26, v10
	v_cvt_pk_bf16_f32 v139, v15, v12
	v_cvt_pk_bf16_f32 v140, v16, v8
	v_cvt_pk_bf16_f32 v141, v18, v0
	v_add_u32_e32 v32, 16, v176
	s_waitcnt vmcnt(0)
	s_waitcnt vmcnt(0) lgkmcnt(0)
	s_barrier
; #define QK_FENCE() __builtin_amdgcn_sched_barrier(0x406)
; DI void qkt12(f32x16& p0, f32x16& p1, const char* Kt, const char* Rt, const int* ko, const int* ro, const bf16x8* qr) {
;   { const f32x16 z = {0.f, 0.f, 0.f, 0.f, 0.f, 0.f, 0.f, 0.f, 0.f, 0.f, 0.f, 0.f, 0.f, 0.f, 0.f, 0.f}; p0 = z; p1 = z; }
;   const char* kp[4] = {Kt + ko[0], Kt + ko[1], Kt + ko[2], Kt + ko[3]};
;   const char* rp[4] = {Rt + ro[0], Rt + ro[1], Rt + ro[2], Rt + ro[3]};
;   bf16x8 ka[2], kb[2];
;   ka[0] = *reinterpret_cast<const bf16x8*>(kp[0]); kb[0] = *reinterpret_cast<const bf16x8*>(kp[0] + 8192);
; #pragma unroll
;   for (int d0 = 0; d0 < 12; ++d0) {
;     if (d0 + 1 < 12) { const int d1 = d0 + 1;
;       if (d1 < 8) { ka[d1 & 1] = *reinterpret_cast<const bf16x8*>(kp[d1 & 3] + (d1 >> 2) * 128); kb[d1 & 1] = *reinterpret_cast<const bf16x8*>(kp[d1 & 3] + (d1 >> 2) * 128 + 8192); }
;       else { ka[d1 & 1] = *reinterpret_cast<const bf16x8*>(rp[d1 - 8]); kb[d1 & 1] = *reinterpret_cast<const bf16x8*>(rp[d1 - 8] + 4096); } }
;     QK_FENCE();
;     p0 = __builtin_amdgcn_mfma_f32_32x32x16_bf16(ka[d0 & 1], qr[d0], p0, 0, 0, 0);
;     p1 = __builtin_amdgcn_mfma_f32_32x32x16_bf16(kb[d0 & 1], qr[d0], p1, 0, 0, 0);
;     QK_FENCE();
;   }
; }
; DI void attn_item_dma(const u16* Qb, const u16* Kh, const u16* Vh, const u16* Rh, u16* Ob, int seq, const float* rope, int pos0, char* lds) {
;     ...
;   int ko[4], ro[4];
; #pragma unroll
;   for (int i = 0; i < 4; ++i) { ko[i] = r32 * 256 + ((i * 32 + hi * 16) ^ ((r32 & 7) << 4)); ro[i] = r32 * 128 + ((i * 32 + hi * 16) ^ (((r32 >> 1) & 7) << 4)); }
	ds_read_b128 v[0:3], v32 offset:16384
	ds_read_b128 v[4:7], v32 offset:24576
	ds_read_b128 v[8:11], v76 offset:16384
	ds_read_b128 v[12:15], v76 offset:24576
	s_waitcnt lgkmcnt(3)
	v_mfma_f32_32x32x16_bf16 v[16:31], v[0:3], v[134:137], 0
	ds_read_b128 v[62:65], v32 offset:16512
	ds_read_b128 v[0:3], v32 offset:24704
	s_add_i32 s2, 16, 0x1e000
	s_cmp_lg_u32 16, -1
	s_mov_b64 s[36:37], 0x80100
	s_mov_b32 s12, 4
	s_waitcnt lgkmcnt(4)
	v_mfma_f32_32x32x16_bf16 v[32:47], v[4:7], v[134:137], 0
	ds_read_b128 v[4:7], v85 offset:16384
	ds_read_b128 v[66:69], v85 offset:24576
	ds_read_b128 v[70:73], v76 offset:16512
	s_waitcnt lgkmcnt(6)
	v_mfma_f32_32x32x16_bf16 v[16:31], v[8:11], v[130:133], v[16:31]
	ds_read_b128 v[8:11], v76 offset:24704
	s_waitcnt lgkmcnt(6)
	v_mfma_f32_32x32x16_bf16 v[32:47], v[12:15], v[130:133], v[32:47]
	ds_read_b128 v[12:15], v87 offset:16384
	ds_read_b128 v[74:77], v87 offset:24576
	ds_read_b128 v[78:81], v85 offset:16512
	s_waitcnt lgkmcnt(6)
	v_mfma_f32_32x32x16_bf16 v[16:31], v[4:7], v[126:129], v[16:31]
	ds_read_b128 v[4:7], v85 offset:24704
	s_waitcnt lgkmcnt(6)
	v_mfma_f32_32x32x16_bf16 v[32:47], v[66:69], v[126:129], v[32:47]
	ds_read_b128 v[66:69], v87 offset:16512
	s_waitcnt lgkmcnt(4)
	v_mfma_f32_32x32x16_bf16 v[16:31], v[12:15], v[114:117], v[16:31]
	ds_read_b128 v[12:15], v87 offset:24704
	s_waitcnt lgkmcnt(4)
	v_mfma_f32_32x32x16_bf16 v[32:47], v[74:77], v[114:117], v[32:47]
	v_mfma_f32_32x32x16_bf16 v[16:31], v[62:65], v[110:113], v[16:31]
	v_lshlrev_b32_e32 v62, 7, v170
	v_and_b32_e32 v63, 0x70, v82
	v_bitop3_b32 v182, v96, v62, v63 bitop3:0xde
	v_bitop3_b32 v183, v83, v62, v63 bitop3:0xde
	v_bitop3_b32 v184, v84, v62, v63 bitop3:0xde
	v_bitop3_b32 v185, v86, v62, v63 bitop3:0xde
	v_mfma_f32_32x32x16_bf16 v[32:47], v[0:3], v[110:113], v[32:47]
	v_mfma_f32_32x32x16_bf16 v[16:31], v[70:73], v[106:109], v[16:31]
	v_mfma_f32_32x32x16_bf16 v[32:47], v[8:11], v[106:109], v[32:47]
	s_waitcnt lgkmcnt(3)
	v_mfma_f32_32x32x16_bf16 v[16:31], v[78:81], v[102:105], v[16:31]
	s_waitcnt lgkmcnt(2)
	v_mfma_f32_32x32x16_bf16 v[32:47], v[4:7], v[102:105], v[32:47]
	v_add_u32_e32 v4, 16, v182
	ds_read_b128 v[0:3], v4 offset:32768
	ds_read_b128 v[4:7], v4 offset:36864
	s_waitcnt lgkmcnt(3)
	v_mfma_f32_32x32x16_bf16 v[16:31], v[66:69], v[98:101], v[16:31]
	v_and_b32_e32 v66, 63, v58
	v_lshlrev_b32_e32 v67, 3, v66
	v_lshlrev_b32_e32 v68, 1, v58
	s_waitcnt lgkmcnt(2)
	v_mfma_f32_32x32x16_bf16 v[32:47], v[12:15], v[98:101], v[32:47]
	v_add_u32_e32 v12, 16, v183
	ds_read_b128 v[8:11], v12 offset:32768
	ds_read_b128 v[12:15], v12 offset:36864
	s_waitcnt lgkmcnt(3)
	v_mfma_f32_32x32x16_bf16 v[16:31], v[0:3], v[122:125], v[16:31]
	s_waitcnt lgkmcnt(2)
	v_mfma_f32_32x32x16_bf16 v[32:47], v[4:7], v[122:125], v[32:47]
	v_add_u32_e32 v4, 16, v184
	ds_read_b128 v[0:3], v4 offset:32768
	ds_read_b128 v[4:7], v4 offset:36864
	s_waitcnt lgkmcnt(3)
	v_mfma_f32_32x32x16_bf16 v[16:31], v[8:11], v[142:145], v[16:31]
	v_and_b32_e32 v8, 0x3fffffc0, v58
	v_lshl_add_u32 v147, v8, 2, s2
	v_and_b32_e32 v8, 0xc0, v175
	s_cselect_b32 s2, 16, 0
	v_lshl_add_u32 v172, v170, 2, v147
	s_waitcnt lgkmcnt(2)
	v_mfma_f32_32x32x16_bf16 v[32:47], v[12:15], v[142:145], v[32:47]
	v_add_u32_e32 v14, 16, v185
	v_and_or_b32 v12, v67, 24, v8
	ds_read_b128 v[8:11], v14 offset:32768
	ds_read_b128 v[62:65], v14 offset:36864
	v_and_b32_e32 v13, 32, v68
	s_waitcnt lgkmcnt(3)
	v_mfma_f32_32x32x16_bf16 v[16:31], v[0:3], v[118:121], v[16:31]
	v_and_b32_e32 v0, 0x100, v67
	v_or3_b32 v0, v12, v13, v0
	v_add_u32_e32 v174, s2, v0
	s_add_i32 s2, 16, 0x14000
	s_waitcnt lgkmcnt(2)
	v_mfma_f32_32x32x16_bf16 v[32:47], v[4:7], v[118:121], v[32:47]
	s_waitcnt lgkmcnt(1)
	v_mfma_f32_32x32x16_bf16 v[16:31], v[8:11], v[138:141], v[16:31]
	v_mov_b64_e32 v[0:1], s[84:85]
	v_mov_b64_e32 v[14:15], s[98:99]
	v_mov_b64_e32 v[2:3], s[86:87]
	v_mov_b64_e32 v[4:5], s[88:89]
	v_mov_b64_e32 v[6:7], s[90:91]
	v_mov_b64_e32 v[8:9], s[92:93]
	v_mov_b64_e32 v[10:11], s[94:95]
	s_waitcnt lgkmcnt(0)
; DI void partialSM(f32x16& p0, f32x16& p1, float& m_reg, float& mn, float& alpha) {
;   constexpr float C = ATT_SCALE * 1.4426950408889634f;
;   float pmax = p0[0];
; #pragma unroll
;   for (int r = 1; r < 16; ++r) pmax = fmaxf(pmax, p0[r]);
; #pragma unroll
;   for (int r = 0; r < 16; ++r) pmax = fmaxf(pmax, p1[r]);
;   { auto rr = __builtin_amdgcn_permlane32_swap(__float_as_uint(pmax), __float_as_uint(pmax), false, false);
;     pmax = fmaxf(__uint_as_float(rr[0]), __uint_as_float(rr[1])); }
;   if (__builtin_expect(__all(pmax - m_reg <= ATT_THR / ATT_SCALE), 1)) { mn = m_reg; alpha = 1.f; }
;   else { mn = fmaxf(m_reg, pmax); alpha = __builtin_amdgcn_exp2f((m_reg - mn) * C); m_reg = mn; }
;   const float mnC = -mn * C;
; #pragma unroll
;   for (int r = 0; r < 16; ++r) p0[r] = fmaf(p0[r], C, mnC);
; #pragma unroll
;   for (int r = 0; r < 16; ++r) p1[r] = fmaf(p1[r], C, mnC);
; #pragma unroll
;   for (int r = 0; r < 16; ++r) p0[r] = __builtin_amdgcn_exp2f(p0[r]);
; }
; DI void attn_item_dma(const u16* Qb, const u16* Kh, const u16* Vh, const u16* Rh, u16* Ob, int seq, const float* rope, int pos0, char* lds) {
;     ...
;   if (2 < NT) DMA(2, 2);
	v_mfma_f32_32x32x16_bf16 v[32:47], v[62:65], v[138:141], v[32:47]
	s_nop 2
	v_max_f32_e32 v62, v17, v17
	v_max_f32_e32 v63, v16, v16
	v_max_f32_e32 v62, v63, v62
	v_max3_f32 v62, v62, v18, v19
	v_max3_f32 v62, v62, v20, v21
	v_max3_f32 v62, v62, v22, v23
	v_max3_f32 v62, v62, v24, v25
	v_max3_f32 v62, v62, v26, v27
	v_max3_f32 v62, v62, v28, v29
	v_max3_f32 v62, v62, v30, v31
	v_max3_f32 v62, v62, v32, v33
	v_max3_f32 v62, v62, v34, v35
	v_max3_f32 v62, v62, v36, v37
	v_max3_f32 v62, v62, v38, v39
	v_max3_f32 v62, v62, v40, v41
	v_add_u32_e32 v65, s2, v175
	v_max3_f32 v62, v62, v42, v43
	v_readfirstlane_b32 s2, v65
	v_max3_f32 v64, v62, v44, v45
	v_lshl_add_u64 v[62:63], v[52:53], 0, s[36:37]
	s_mov_b32 m0, s2
	s_mov_b64 s[36:37], 0xa0100
	global_load_lds_dwordx4 v[62:63], off
	v_add_u32_e32 v62, 0x2000, v65
	v_lshl_add_u64 v[52:53], v[52:53], 0, s[36:37]
	v_readfirstlane_b32 s2, v62
	v_add_u32_e32 v62, 0x4000, v65
	s_mov_b32 m0, s2
	v_readfirstlane_b32 s2, v62
	global_load_lds_dwordx4 v[52:53], off
	v_lshl_add_u64 v[52:53], v[54:55], 0, s[66:67]
	s_mov_b32 m0, s2
	s_mov_b64 s[36:37], 0xa0000
	global_load_lds_dwordx4 v[52:53], off
	v_lshl_add_u64 v[52:53], v[54:55], 0, s[36:37]
	v_add_u32_e32 v54, 0x6000, v65
	v_mov_b64_e32 v[12:13], s[96:97]
	v_readfirstlane_b32 s2, v54
	v_add_u32_e32 v54, 0x8000, v65
	s_mov_b32 m0, s2
	v_readfirstlane_b32 s2, v54
	global_load_lds_dwordx4 v[52:53], off
	v_lshl_add_u64 v[52:53], v[56:57], 0, s[68:69]
	s_mov_b32 m0, s2
	s_movk_i32 s96, 0x7b00
	global_load_lds_dwordx4 v[52:53], off
	v_max3_f32 v52, v64, v46, v47
	v_mov_b32_e32 v53, v52
	s_nop 1
	v_permlane32_swap_b32_e32 v52, v53
	v_max_f32_e32 v53, v53, v53
	v_max_f32_e32 v52, v52, v52
	v_max_f32_e32 v52, v52, v53
	v_add_f32_e32 v53, 0x7149f2ca, v52
	v_cmp_ge_f32_e32 vcc, s65, v53
	s_cmp_eq_u64 vcc, exec
	v_max_f32_e32 v52, 0xf149f2ca, v52
	s_cselect_b64 vcc, -1, 0
	v_mov_b32_e32 v53, 0xf149f2ca
	v_cndmask_b32_e32 v187, v52, v53, vcc
	v_sub_f32_e32 v54, 0xf149f2ca, v52
	v_mul_f32_e32 v52, 0xbdd53b94, v187
	v_fmamk_f32 v200, v16, 0x3dd53b94, v52
	v_fmamk_f32 v202, v17, 0x3dd53b94, v52
	v_fmamk_f32 v201, v18, 0x3dd53b94, v52
	v_fmamk_f32 v204, v19, 0x3dd53b94, v52
	v_fmamk_f32 v203, v20, 0x3dd53b94, v52
	v_fmamk_f32 v206, v21, 0x3dd53b94, v52
	v_fmamk_f32 v205, v22, 0x3dd53b94, v52
	v_fmamk_f32 v207, v23, 0x3dd53b94, v52
	v_fmamk_f32 v192, v24, 0x3dd53b94, v52
	v_fmamk_f32 v194, v25, 0x3dd53b94, v52
	v_fmamk_f32 v193, v26, 0x3dd53b94, v52
	v_fmamk_f32 v196, v27, 0x3dd53b94, v52
	v_fmamk_f32 v195, v28, 0x3dd53b94, v52
	v_mul_f32_e32 v54, 0x3dd53b94, v54
	v_fmamk_f32 v198, v29, 0x3dd53b94, v52
	v_exp_f32_e32 v54, v54
	v_fmamk_f32 v197, v30, 0x3dd53b94, v52
	s_add_u32 s42, s26, s42
	v_pk_fma_f32 v[158:159], v[46:47], s[70:71], v[52:53] op_sel_hi:[1,0,0]
	v_pk_fma_f32 v[164:165], v[44:45], s[70:71], v[52:53] op_sel_hi:[1,0,0]
	v_pk_fma_f32 v[168:169], v[42:43], s[70:71], v[52:53] op_sel_hi:[1,0,0]
	v_pk_fma_f32 v[154:155], v[40:41], s[70:71], v[52:53] op_sel_hi:[1,0,0]
	v_pk_fma_f32 v[156:157], v[38:39], s[70:71], v[52:53] op_sel_hi:[1,0,0]
	v_pk_fma_f32 v[160:161], v[36:37], s[70:71], v[52:53] op_sel_hi:[1,0,0]
	v_pk_fma_f32 v[162:163], v[34:35], s[70:71], v[52:53] op_sel_hi:[1,0,0]
	v_pk_fma_f32 v[166:167], v[32:33], s[70:71], v[52:53] op_sel_hi:[1,0,0]
	v_fmamk_f32 v199, v31, 0x3dd53b94, v52
	s_addc_u32 s43, s27, s43
	s_or_b32 s2, s38, s6
	v_or3_b32 v16, v61, v60, v59
	v_and_b32_e32 v18, 3, v58
	v_lshlrev_b32_e32 v16, 12, v16
	v_and_b32_e32 v17, 0xc0, v68
	v_lshlrev_b32_e32 v18, 4, v18
	s_add_u32 s6, s26, s2
	v_or3_b32 v16, v16, v17, v18
	v_mov_b32_e32 v17, v97
	s_addc_u32 s7, s27, s39
	v_cndmask_b32_e64 v186, v54, 1.0, vcc
	v_lshl_add_u64 v[148:149], s[42:43], 0, v[50:51]
	v_lshl_add_u64 v[150:151], s[6:7], 0, v[16:17]
	v_lshl_add_u64 v[152:153], s[6:7], 0, v[48:49]
	v_mov_b64_e32 v[62:63], v[14:15]
	v_mov_b64_e32 v[46:47], v[14:15]
	v_mov_b64_e32 v[30:31], v[14:15]
	s_movk_i32 s95, 0x104
	v_cmp_gt_u32_e64 s[36:37], 32, v66
	v_mov_b64_e32 v[60:61], v[12:13]
	v_mov_b64_e32 v[58:59], v[10:11]
	v_mov_b64_e32 v[56:57], v[8:9]
	v_mov_b64_e32 v[54:55], v[6:7]
	v_mov_b64_e32 v[52:53], v[4:5]
	v_mov_b64_e32 v[50:51], v[2:3]
	v_mov_b64_e32 v[48:49], v[0:1]
	v_mov_b64_e32 v[44:45], v[12:13]
	v_mov_b64_e32 v[42:43], v[10:11]
	v_mov_b64_e32 v[40:41], v[8:9]
	v_mov_b64_e32 v[38:39], v[6:7]
	v_mov_b64_e32 v[36:37], v[4:5]
	v_mov_b64_e32 v[34:35], v[2:3]
	v_mov_b64_e32 v[32:33], v[0:1]
	v_mov_b64_e32 v[28:29], v[12:13]
	v_mov_b64_e32 v[26:27], v[10:11]
	v_mov_b64_e32 v[24:25], v[8:9]
	v_mov_b64_e32 v[22:23], v[6:7]
	v_mov_b64_e32 v[20:21], v[4:5]
	v_mov_b64_e32 v[18:19], v[2:3]
	v_mov_b64_e32 v[16:17], v[0:1]
